# LayerNorm phases: gamma/beta loaded once before the row loop instead of 16 load-wait round trips per iteration
# speedup vs baseline: 1.0034x; 1.0034x over previous
.LBB0_75:
	s_cmp_lg_u32 s65, 0
	s_cbranch_scc0 .LBB0_83
	s_add_i32 s0, s65, -1
	s_mul_hi_i32 s1, s0, 0x38e38e39
	s_lshr_b32 s2, s1, 31
	s_ashr_i32 s1, s1, 1
	s_add_i32 s4, s1, s2
	s_mul_i32 s1, s4, 9
	s_ashr_i32 s5, s4, 31
	s_sub_i32 s25, s0, s1
	v_writelane_b32 v255, s4, 36
	s_cmp_lt_i32 s25, 4
	s_mov_b64 s[0:1], -1
	v_writelane_b32 v255, s5, 37
	s_cbranch_scc1 .LBB0_229
	v_readlane_b32 s0, v255, 36
	v_readlane_b32 s1, v255, 37
	s_lshl_b32 s0, s0, 10
	s_ashr_i32 s1, s0, 31
	v_readlane_b32 s40, v253, 18
	s_lshl_b64 s[0:1], s[0:1], 2
	v_readlane_b32 s42, v253, 20
	v_readlane_b32 s43, v253, 21
	s_add_u32 s34, s42, s0
	v_readlane_b32 s44, v253, 22
	s_addc_u32 s35, s43, s1
	v_readlane_b32 s41, v253, 19
	v_readlane_b32 s45, v253, 23
	s_add_u32 s40, s44, s0
	s_addc_u32 s41, s45, s1
	s_cmp_lt_i32 s25, 6
	s_mov_b64 s[28:29], -1
	v_readlane_b32 s46, v253, 24
	v_readlane_b32 s47, v253, 25
	v_readlane_b32 s48, v253, 26
	v_readlane_b32 s49, v253, 27
	v_readlane_b32 s50, v253, 28
	v_readlane_b32 s51, v253, 29
	v_readlane_b32 s52, v253, 30
	v_readlane_b32 s53, v253, 31
	v_readlane_b32 s54, v253, 32
	v_readlane_b32 s55, v253, 33
	s_cbranch_scc1 .LBB0_141
	s_cmp_lt_i32 s25, 7
	s_cbranch_scc1 .LBB0_132
	s_cmp_lt_i32 s25, 8
	s_cbranch_scc1 .LBB0_123
	s_cmp_eq_u32 s25, 8
	s_cbranch_scc0 .LBB0_122
	v_mov_b32_e32 v0, v169
	s_waitcnt vmcnt(7)
	v_mov_b32_e32 v2, v169
	v_readlane_b32 s2, v254, 32
	s_nop 1
	v_add_u32_e32 v2, s2, v2
	s_mov_b32 s2, 0x200000
	v_cmp_gt_u32_e32 vcc, s2, v2
	s_and_saveexec_b64 s[28:29], vcc
	s_cbranch_execz .LBB0_121
	s_load_dword s2, s[22:23], 0x0
	s_add_i32 s4, s65, -10
	v_readlane_b32 s48, v253, 18
	v_readlane_b32 s60, v253, 30
	v_readlane_b32 s61, v253, 31
	s_waitcnt lgkmcnt(0)
	s_lshl_b32 s42, s2, 2
	s_cmp_gt_u32 s4, 8
	s_cselect_b64 s[44:45], -1, 0
	s_add_u32 s4, s60, s0
	v_readlane_b32 s58, v253, 28
	s_addc_u32 s5, s61, s1
	v_lshrrev_b32_e32 v48, 6, v2
	v_and_b32_e32 v2, 63, v0
	v_readlane_b32 s59, v253, 29
	s_add_u32 s0, s58, s0
	s_addc_u32 s1, s59, s1
	v_lshlrev_b32_e32 v0, 4, v2
	v_readlane_b32 s62, v253, 32
	v_readlane_b32 s63, v253, 33
	v_cmp_eq_u32_e32 vcc, 0, v2
	v_lshl_add_u64 v[36:37], s[0:1], 0, v[0:1]
	v_readlane_b32 s0, v254, 28
	v_lshl_add_u64 v[34:35], s[62:63], 0, v[0:1]
	s_and_b64 s[46:47], s[44:45], vcc
	v_lshl_add_u64 v[38:39], s[4:5], 0, v[0:1]
	v_lshlrev_b32_e32 v0, 3, v2
	v_readlane_b32 s1, v254, 29
	v_cmp_lt_i32_e32 vcc, v184, v183
	v_readlane_b32 s49, v253, 19
	v_lshl_add_u64 v[40:41], s[0:1], 0, v[0:1]
	v_cndmask_b32_e32 v0, v182, v184, vcc
	v_cmp_lt_i32_e32 vcc, v185, v183
	v_lshlrev_b32_e32 v0, 2, v0
	s_ashr_i32 s43, s42, 31
	v_cndmask_b32_e32 v2, v182, v185, vcc
	v_lshlrev_b32_e32 v64, 2, v2
	v_xor_b32_e32 v2, 8, v182
	v_cmp_lt_i32_e32 vcc, v2, v183
	s_mov_b64 s[48:49], 0
	v_readlane_b32 s50, v253, 20
	v_cndmask_b32_e32 v2, v182, v2, vcc
	v_lshlrev_b32_e32 v65, 2, v2
	v_xor_b32_e32 v2, 4, v182
	v_cmp_lt_i32_e32 vcc, v2, v183
	v_readlane_b32 s51, v253, 21
	v_readlane_b32 s52, v253, 22
	v_cndmask_b32_e32 v2, v182, v2, vcc
	v_lshlrev_b32_e32 v66, 2, v2
	v_xor_b32_e32 v2, 2, v182
	v_cmp_lt_i32_e32 vcc, v2, v183
	v_readlane_b32 s53, v253, 23
	v_readlane_b32 s54, v253, 24
	v_cndmask_b32_e32 v2, v182, v2, vcc
	v_lshlrev_b32_e32 v67, 2, v2
	v_xor_b32_e32 v2, 1, v182
	v_cmp_lt_i32_e32 vcc, v2, v183
	v_readlane_b32 s55, v253, 25
	v_readlane_b32 s56, v253, 26
	v_cndmask_b32_e32 v2, v182, v2, vcc
	v_lshlrev_b32_e32 v68, 2, v2
	v_readlane_b32 s57, v253, 27
	global_load_dwordx4 v[100:103], v[36:37], off
	global_load_dwordx4 v[116:119], v[38:39], off
	global_load_dwordx4 v[104:107], v[36:37], off offset:1024
	global_load_dwordx4 v[120:123], v[38:39], off offset:1024
	global_load_dwordx4 v[108:111], v[36:37], off offset:2048
	global_load_dwordx4 v[124:127], v[38:39], off offset:2048
	global_load_dwordx4 v[112:115], v[36:37], off offset:3072
	global_load_dwordx4 v[128:131], v[38:39], off offset:3072
	s_waitcnt vmcnt(0)
	s_branch .LBB0_85

.LBB0_88:
	s_or_b64 exec, exec, s[0:1]
	s_nop 1
	v_lshlrev_b64 v[8:9], 10, v[48:49]
	v_pk_mul_f32 v[12:13], v[62:63], v[4:5] op_sel_hi:[1,0]
	v_pk_mul_f32 v[16:17], v[30:31], v[4:5] op_sel_hi:[1,0]
	s_mov_b64 s[0:1], -1
	s_and_b64 vcc, exec, s[44:45]
	v_lshl_add_u64 v[8:9], v[8:9], 1, v[40:41]
	v_pk_fma_f32 v[30:31], v[12:13], v[102:103], v[118:119]
	v_pk_fma_f32 v[28:29], v[16:17], v[100:101], v[116:117]
	s_cbranch_vccz .LBB0_90
	v_cvt_pk_bf16_f32 v12, v28, v29
	v_cvt_pk_bf16_f32 v13, v30, v31
	global_store_dwordx2 v[8:9], v[12:13], off
	s_mov_b64 s[0:1], 0

.LBB0_92:
	s_nop 1
	v_mov_b32_e32 v5, v4
	v_mov_b32_e32 v12, v4
	v_mov_b32_e32 v13, v4
	v_pk_mul_f32 v[12:13], v[58:59], v[12:13]
	v_pk_mul_f32 v[16:17], v[26:27], v[4:5]
	s_mov_b64 s[0:1], -1
	s_and_b64 vcc, exec, s[44:45]
	v_pk_fma_f32 v[26:27], v[12:13], v[106:107], v[122:123]
	v_pk_fma_f32 v[24:25], v[16:17], v[104:105], v[120:121]
	s_cbranch_vccz .LBB0_94
	v_cvt_pk_bf16_f32 v12, v24, v25
	v_cvt_pk_bf16_f32 v13, v26, v27
	global_store_dwordx2 v[8:9], v[12:13], off offset:512
	s_mov_b64 s[0:1], 0

.LBB0_96:
	s_nop 1
	v_mov_b32_e32 v12, v4
	v_mov_b32_e32 v13, v4
	v_pk_mul_f32 v[16:17], v[22:23], v[4:5]
	v_pk_mul_f32 v[12:13], v[56:57], v[12:13]
	s_mov_b64 s[0:1], -1
	s_and_b64 vcc, exec, s[44:45]
	v_pk_fma_f32 v[22:23], v[12:13], v[110:111], v[126:127]
	v_pk_fma_f32 v[20:21], v[16:17], v[108:109], v[124:125]
	s_cbranch_vccz .LBB0_98
	v_cvt_pk_bf16_f32 v12, v20, v21
	v_cvt_pk_bf16_f32 v13, v22, v23
	global_store_dwordx2 v[8:9], v[12:13], off offset:1024
	s_mov_b64 s[0:1], 0

.LBB0_100:
	s_nop 1
	v_mov_b32_e32 v12, v4
	v_mov_b32_e32 v13, v4
	v_pk_mul_f32 v[4:5], v[18:19], v[4:5]
	v_pk_mul_f32 v[12:13], v[54:55], v[12:13]
	s_mov_b64 s[0:1], -1
	s_and_b64 vcc, exec, s[44:45]
	v_pk_fma_f32 v[18:19], v[12:13], v[114:115], v[130:131]
	v_pk_fma_f32 v[16:17], v[4:5], v[112:113], v[128:129]
	s_cbranch_vccz .LBB0_103
	v_cvt_pk_bf16_f32 v4, v16, v17
	v_cvt_pk_bf16_f32 v5, v18, v19
	global_store_dwordx2 v[8:9], v[4:5], off offset:1536
	s_cbranch_execz .LBB0_104

.LBB0_105:
	s_nop 1
	v_pk_mul_f32 v[4:5], v[52:53], v[60:61] op_sel_hi:[1,0]
	v_pk_mul_f32 v[8:9], v[14:15], v[60:61] op_sel_hi:[1,0]
	s_mov_b64 s[38:39], -1
	s_and_b64 vcc, exec, s[44:45]
	v_ashrrev_i32_e32 v43, 31, v42
	v_pk_fma_f32 v[14:15], v[4:5], v[102:103], v[118:119]
	v_pk_fma_f32 v[12:13], v[8:9], v[100:101], v[116:117]
	s_cbranch_vccz .LBB0_107
	v_lshlrev_b64 v[8:9], 11, v[42:43]
	v_cvt_pk_bf16_f32 v4, v12, v13
	v_cvt_pk_bf16_f32 v5, v14, v15
	v_lshl_add_u64 v[8:9], v[40:41], 0, v[8:9]
	global_store_dwordx2 v[8:9], v[4:5], off
	s_mov_b64 s[38:39], 0

.LBB0_109:
	s_nop 1
	v_mov_b32_e32 v61, v60
	v_mov_b32_e32 v4, v60
	v_mov_b32_e32 v5, v60
	v_pk_mul_f32 v[4:5], v[50:51], v[4:5]
	v_pk_mul_f32 v[8:9], v[10:11], v[60:61]
	s_mov_b64 s[38:39], -1
	s_and_b64 vcc, exec, s[44:45]
	v_pk_fma_f32 v[10:11], v[4:5], v[106:107], v[122:123]
	v_pk_fma_f32 v[8:9], v[8:9], v[104:105], v[120:121]
	s_cbranch_vccz .LBB0_111
	v_lshlrev_b64 v[12:13], 11, v[42:43]
	v_cvt_pk_bf16_f32 v4, v8, v9
	v_cvt_pk_bf16_f32 v5, v10, v11
	v_lshl_add_u64 v[12:13], v[40:41], 0, v[12:13]
	global_store_dwordx2 v[12:13], v[4:5], off offset:512
	s_mov_b64 s[38:39], 0

.LBB0_113:
	s_nop 1
	v_mov_b32_e32 v4, v60
	v_mov_b32_e32 v5, v60
	v_pk_mul_f32 v[16:17], v[6:7], v[60:61]
	v_pk_mul_f32 v[4:5], v[46:47], v[4:5]
	s_mov_b64 s[38:39], -1
	s_and_b64 vcc, exec, s[44:45]
	v_pk_fma_f32 v[6:7], v[4:5], v[110:111], v[126:127]
	v_pk_fma_f32 v[4:5], v[16:17], v[108:109], v[124:125]
	s_cbranch_vccz .LBB0_115
	v_lshlrev_b64 v[10:11], 11, v[42:43]
	v_cvt_pk_bf16_f32 v8, v4, v5
	v_cvt_pk_bf16_f32 v9, v6, v7
	v_lshl_add_u64 v[10:11], v[40:41], 0, v[10:11]
	global_store_dwordx2 v[10:11], v[8:9], off offset:1024
	s_mov_b64 s[38:39], 0

.LBB0_117:
	s_nop 1
	v_mov_b32_e32 v4, v60
	v_mov_b32_e32 v5, v60
	v_pk_mul_f32 v[2:3], v[2:3], v[60:61]
	v_pk_mul_f32 v[4:5], v[32:33], v[4:5]
	s_mov_b64 s[38:39], -1
	s_and_b64 vcc, exec, s[44:45]
	v_pk_fma_f32 v[4:5], v[4:5], v[114:115], v[130:131]
	v_pk_fma_f32 v[2:3], v[2:3], v[112:113], v[128:129]
	s_cbranch_vccz .LBB0_119
	v_lshlrev_b64 v[8:9], 11, v[42:43]
	v_cvt_pk_bf16_f32 v6, v2, v3
	v_cvt_pk_bf16_f32 v7, v4, v5
	v_lshl_add_u64 v[8:9], v[40:41], 0, v[8:9]
	global_store_dwordx2 v[8:9], v[6:7], off offset:1536
	s_mov_b64 s[38:39], 0

.LBB0_149:
	s_or_b64 exec, exec, s[0:1]
	s_nop 1
	v_pk_mul_f32 v[32:33], v[32:33], v[0:1] op_sel_hi:[1,0]
	v_pk_mul_f32 v[30:31], v[30:31], v[0:1] op_sel_hi:[1,0]
	v_lshlrev_b64 v[44:45], 10, v[44:45]
	v_lshl_add_u64 v[44:45], v[44:45], 1, v[40:41]
	v_pk_mul_f32 v[28:29], v[28:29], v[0:1] op_sel_hi:[1,0]
	v_pk_mul_f32 v[26:27], v[26:27], v[0:1] op_sel_hi:[1,0]
	v_pk_mul_f32 v[24:25], v[24:25], v[0:1] op_sel_hi:[1,0]
	v_pk_mul_f32 v[22:23], v[22:23], v[0:1] op_sel_hi:[1,0]
	v_pk_mul_f32 v[20:21], v[20:21], v[0:1] op_sel_hi:[1,0]
	v_pk_mul_f32 v[18:19], v[18:19], v[0:1] op_sel_hi:[1,0]
	v_pk_fma_f32 v[32:33], v[32:33], v[102:103], v[118:119]
	v_pk_fma_f32 v[30:31], v[30:31], v[100:101], v[116:117]
	s_nop 0
	v_cvt_pk_bf16_f32 v30, v30, v31
	v_cvt_pk_bf16_f32 v31, v32, v33
	global_store_dwordx2 v[44:45], v[30:31], off
	s_nop 1
	v_pk_fma_f32 v[28:29], v[28:29], v[106:107], v[122:123]
	v_pk_fma_f32 v[26:27], v[26:27], v[104:105], v[120:121]
	s_nop 0
	v_cvt_pk_bf16_f32 v26, v26, v27
	v_cvt_pk_bf16_f32 v27, v28, v29
	global_store_dwordx2 v[44:45], v[26:27], off offset:512
	s_nop 1
	v_pk_fma_f32 v[24:25], v[24:25], v[110:111], v[126:127]
	v_pk_fma_f32 v[22:23], v[22:23], v[108:109], v[124:125]
	s_nop 0
	v_cvt_pk_bf16_f32 v22, v22, v23
	v_cvt_pk_bf16_f32 v23, v24, v25
	global_store_dwordx2 v[44:45], v[22:23], off offset:1024
	s_nop 1
	v_pk_fma_f32 v[20:21], v[20:21], v[114:115], v[130:131]
	v_pk_fma_f32 v[18:19], v[18:19], v[112:113], v[128:129]
	s_nop 0
	v_cvt_pk_bf16_f32 v18, v18, v19
	v_cvt_pk_bf16_f32 v19, v20, v21
	global_store_dwordx2 v[44:45], v[18:19], off offset:1536
	s_and_saveexec_b64 s[0:1], s[38:39]
	s_cbranch_execz .LBB0_145
	s_nop 1
	v_mov_b32_e32 v0, v47
	v_pk_mul_f32 v[16:17], v[16:17], v[0:1] op_sel_hi:[1,0]
	v_pk_mul_f32 v[14:15], v[14:15], v[0:1] op_sel_hi:[1,0]
	v_ashrrev_i32_e32 v43, 31, v42
	v_pk_mul_f32 v[12:13], v[12:13], v[0:1] op_sel_hi:[1,0]
	v_pk_mul_f32 v[10:11], v[10:11], v[0:1] op_sel_hi:[1,0]
	v_pk_mul_f32 v[8:9], v[8:9], v[0:1] op_sel_hi:[1,0]
	v_pk_mul_f32 v[6:7], v[6:7], v[0:1] op_sel_hi:[1,0]
	v_pk_mul_f32 v[4:5], v[4:5], v[0:1] op_sel_hi:[1,0]
	v_pk_mul_f32 v[2:3], v[2:3], v[0:1] op_sel_hi:[1,0]
	v_pk_fma_f32 v[16:17], v[16:17], v[102:103], v[118:119]
	v_pk_fma_f32 v[14:15], v[14:15], v[100:101], v[116:117]
	s_nop 0
	v_cvt_pk_bf16_f32 v14, v14, v15
	v_cvt_pk_bf16_f32 v15, v16, v17
	v_lshlrev_b64 v[16:17], 11, v[42:43]
	v_lshl_add_u64 v[22:23], v[40:41], 0, v[16:17]
	global_store_dwordx2 v[22:23], v[14:15], off
	s_nop 1
	v_pk_fma_f32 v[12:13], v[12:13], v[106:107], v[122:123]
	v_pk_fma_f32 v[10:11], v[10:11], v[104:105], v[120:121]
	s_nop 0
	v_cvt_pk_bf16_f32 v10, v10, v11
	v_cvt_pk_bf16_f32 v11, v12, v13
	global_store_dwordx2 v[22:23], v[10:11], off offset:512
	s_nop 1
	v_pk_fma_f32 v[8:9], v[8:9], v[110:111], v[126:127]
	v_pk_fma_f32 v[6:7], v[6:7], v[108:109], v[124:125]
	s_nop 0
	v_cvt_pk_bf16_f32 v6, v6, v7
	v_cvt_pk_bf16_f32 v7, v8, v9
	global_store_dwordx2 v[22:23], v[6:7], off offset:1024
	s_nop 1
	v_pk_fma_f32 v[4:5], v[4:5], v[114:115], v[130:131]
	v_pk_fma_f32 v[2:3], v[2:3], v[112:113], v[128:129]
	s_nop 0
	v_cvt_pk_bf16_f32 v2, v2, v3
	v_cvt_pk_bf16_f32 v3, v4, v5
	global_store_dwordx2 v[22:23], v[2:3], off offset:1536
	s_branch .LBB0_145
